# v55 + residual-tile L2 prefetch one K iteration before the ResNorm epilogue + gate_fixup loads of all six column steps batched
# speedup vs baseline: 1.0161x; 1.0013x over previous
.LBB0_797:
	s_cmp_gt_i32 s90, 31
	s_cselect_b64 s[22:23], -1, 0
	s_and_b64 s[0:1], s[0:1], s[22:23]
	s_andn2_b64 vcc, exec, s[0:1]
	s_cbranch_vccnz .LBB0_808
	s_movk_i32 s0, 0xb00
	v_cmp_gt_i32_e32 vcc, s0, v192
	s_and_saveexec_b64 s[0:1], vcc
	s_cbranch_execz .LBB0_807
	s_sub_i32 s22, s90, 32
	s_cmp_eq_u32 s55, 16
	s_mul_hi_u32 s26, s22, 0x10800
	s_mul_i32 s33, s22, 0x10800
	s_cselect_b32 s22, 0x8400, 0
	s_cselect_b32 s34, 0x2c00, 0
	s_add_u32 s22, s68, s22
	s_addc_u32 s23, s69, 0
	s_add_u32 s36, s70, s34
	s_addc_u32 s37, s71, 0
	s_and_b32 s34, s90, 3
	s_cmp_lg_u32 s34, 0
	s_cselect_b64 s[38:39], -1, 0
	s_lshl_b32 s35, s90, 8
	s_cmp_lg_u32 s34, 3
	s_cselect_b64 s[40:41], -1, 0
	s_add_u32 s60, s78, s33
	s_mul_i32 s42, s90, 0x160000
	s_addc_u32 s61, s79, s26
	v_readlane_b32 s44, v253, 8
	s_mul_hi_u32 s35, s35, 0x1600
	v_readlane_b32 s45, v253, 9
	s_add_u32 s34, s44, s42
	v_ashrrev_i32_e32 v193, 31, v192
	s_addc_u32 s35, s45, s35
	v_add_u32_e32 v8, 0xfffffe00, v192
	v_lshlrev_b64 v[0:1], 2, v[192:193]
	s_movk_i32 s42, 0x210
	v_lshl_add_u64 v[2:3], v[192:193], 1, s[34:35]
	s_mov_b64 s[62:63], 0
	s_add_u32 s100, s60, 0xfdfa800
	s_addc_u32 s101, s61, 0
	s_mov_b64 s[34:35], exec
	global_load_dword v16, v0, s[22:23]
	v_add_u32_e32 v6, 0x2c00, v0
	global_load_dword v18, v6, s[22:23]
	v_add_u32_e32 v6, 0x5800, v0
	global_load_dword v17, v6, s[22:23]
	global_load_dword v19, v0, s[36:37]
	s_and_b64 vcc, exec, s[38:39]
	s_cbranch_vccz .Lgf_h2l_0
	global_load_dword v20, v0, s[100:101]
	v_add_u32_e32 v6, 0x5800, v0
	global_load_dword v22, v6, s[100:101]
	v_add_u32_e32 v6, 0x8400, v0
	global_load_dword v21, v6, s[100:101]
	v_add_u32_e32 v6, 0xb000, v0
	global_load_dword v23, v6, s[100:101]
.Lgf_h2l_0:
	s_and_b64 vcc, exec, s[40:41]
	s_cbranch_vccz .Lgf_c_0
	v_add_u32_e32 v6, 0xdc00, v0
	global_load_dword v24, v6, s[100:101]
	v_add_u32_e32 v6, 0x10800, v0
	global_load_dword v26, v6, s[100:101]
	v_add_u32_e32 v6, 0x16000, v0
	global_load_dword v25, v6, s[100:101]
	v_add_u32_e32 v6, 0x13400, v0
	global_load_dword v27, v6, s[100:101]
.Lgf_c_0:
	v_add_u32_e32 v0, 0x800, v0
	global_load_dword v28, v0, s[22:23]
	v_add_u32_e32 v6, 0x2c00, v0
	global_load_dword v30, v6, s[22:23]
	v_add_u32_e32 v6, 0x5800, v0
	global_load_dword v29, v6, s[22:23]
	global_load_dword v31, v0, s[36:37]
	s_and_b64 vcc, exec, s[38:39]
	s_cbranch_vccz .Lgf_h2l_1
	global_load_dword v32, v0, s[100:101]
	v_add_u32_e32 v6, 0x5800, v0
	global_load_dword v34, v6, s[100:101]
	v_add_u32_e32 v6, 0x8400, v0
	global_load_dword v33, v6, s[100:101]
	v_add_u32_e32 v6, 0xb000, v0
	global_load_dword v35, v6, s[100:101]
.Lgf_h2l_1:
	s_and_b64 vcc, exec, s[40:41]
	s_cbranch_vccz .Lgf_c_1
	v_add_u32_e32 v6, 0xdc00, v0
	global_load_dword v36, v6, s[100:101]
	v_add_u32_e32 v6, 0x10800, v0
	global_load_dword v38, v6, s[100:101]
	v_add_u32_e32 v6, 0x16000, v0
	global_load_dword v37, v6, s[100:101]
	v_add_u32_e32 v6, 0x13400, v0
	global_load_dword v39, v6, s[100:101]
.Lgf_c_1:
	v_add_u32_e32 v0, 0x800, v0
	global_load_dword v40, v0, s[22:23]
	v_add_u32_e32 v6, 0x2c00, v0
	global_load_dword v42, v6, s[22:23]
	v_add_u32_e32 v6, 0x5800, v0
	global_load_dword v41, v6, s[22:23]
	global_load_dword v43, v0, s[36:37]
	s_and_b64 vcc, exec, s[38:39]
	s_cbranch_vccz .Lgf_h2l_2
	global_load_dword v44, v0, s[100:101]
	v_add_u32_e32 v6, 0x5800, v0
	global_load_dword v46, v6, s[100:101]
	v_add_u32_e32 v6, 0x8400, v0
	global_load_dword v45, v6, s[100:101]
	v_add_u32_e32 v6, 0xb000, v0
	global_load_dword v47, v6, s[100:101]
.Lgf_h2l_2:
	s_and_b64 vcc, exec, s[40:41]
	s_cbranch_vccz .Lgf_c_2
	v_add_u32_e32 v6, 0xdc00, v0
	global_load_dword v48, v6, s[100:101]
	v_add_u32_e32 v6, 0x10800, v0
	global_load_dword v50, v6, s[100:101]
	v_add_u32_e32 v6, 0x16000, v0
	global_load_dword v49, v6, s[100:101]
	v_add_u32_e32 v6, 0x13400, v0
	global_load_dword v51, v6, s[100:101]
.Lgf_c_2:
	v_add_u32_e32 v0, 0x800, v0
	global_load_dword v52, v0, s[22:23]
	v_add_u32_e32 v6, 0x2c00, v0
	global_load_dword v54, v6, s[22:23]
	v_add_u32_e32 v6, 0x5800, v0
	global_load_dword v53, v6, s[22:23]
	global_load_dword v55, v0, s[36:37]
	s_and_b64 vcc, exec, s[38:39]
	s_cbranch_vccz .Lgf_h2l_3
	global_load_dword v56, v0, s[100:101]
	v_add_u32_e32 v6, 0x5800, v0
	global_load_dword v58, v6, s[100:101]
	v_add_u32_e32 v6, 0x8400, v0
	global_load_dword v57, v6, s[100:101]
	v_add_u32_e32 v6, 0xb000, v0
	global_load_dword v59, v6, s[100:101]
.Lgf_h2l_3:
	s_and_b64 vcc, exec, s[40:41]
	s_cbranch_vccz .Lgf_c_3
	v_add_u32_e32 v6, 0xdc00, v0
	global_load_dword v60, v6, s[100:101]
	v_add_u32_e32 v6, 0x10800, v0
	global_load_dword v62, v6, s[100:101]
	v_add_u32_e32 v6, 0x16000, v0
	global_load_dword v61, v6, s[100:101]
	v_add_u32_e32 v6, 0x13400, v0
	global_load_dword v63, v6, s[100:101]
.Lgf_c_3:
	v_add_u32_e32 v0, 0x800, v0
	global_load_dword v64, v0, s[22:23]
	v_add_u32_e32 v6, 0x2c00, v0
	global_load_dword v66, v6, s[22:23]
	v_add_u32_e32 v6, 0x5800, v0
	global_load_dword v65, v6, s[22:23]
	global_load_dword v67, v0, s[36:37]
	s_and_b64 vcc, exec, s[38:39]
	s_cbranch_vccz .Lgf_h2l_4
	global_load_dword v68, v0, s[100:101]
	v_add_u32_e32 v6, 0x5800, v0
	global_load_dword v70, v6, s[100:101]
	v_add_u32_e32 v6, 0x8400, v0
	global_load_dword v69, v6, s[100:101]
	v_add_u32_e32 v6, 0xb000, v0
	global_load_dword v71, v6, s[100:101]
.Lgf_h2l_4:
	s_and_b64 vcc, exec, s[40:41]
	s_cbranch_vccz .Lgf_c_4
	v_add_u32_e32 v6, 0xdc00, v0
	global_load_dword v72, v6, s[100:101]
	v_add_u32_e32 v6, 0x10800, v0
	global_load_dword v74, v6, s[100:101]
	v_add_u32_e32 v6, 0x16000, v0
	global_load_dword v73, v6, s[100:101]
	v_add_u32_e32 v6, 0x13400, v0
	global_load_dword v75, v6, s[100:101]
.Lgf_c_4:
	v_add_u32_e32 v0, 0x800, v0
	v_cmp_gt_u32_e32 vcc, 0x100, v192
	s_nop 1
	s_and_b64 exec, exec, vcc
	s_cbranch_execz .Lgf_ld_done
	global_load_dword v76, v0, s[22:23]
	v_add_u32_e32 v6, 0x2c00, v0
	global_load_dword v78, v6, s[22:23]
	v_add_u32_e32 v6, 0x5800, v0
	global_load_dword v77, v6, s[22:23]
	global_load_dword v79, v0, s[36:37]
	s_and_b64 vcc, exec, s[38:39]
	s_cbranch_vccz .Lgf_h2l_5
	global_load_dword v80, v0, s[100:101]
	v_add_u32_e32 v6, 0x5800, v0
	global_load_dword v82, v6, s[100:101]
	v_add_u32_e32 v6, 0x8400, v0
	global_load_dword v81, v6, s[100:101]
	v_add_u32_e32 v6, 0xb000, v0
	global_load_dword v83, v6, s[100:101]
.Lgf_h2l_5:
	s_and_b64 vcc, exec, s[40:41]
	s_cbranch_vccz .Lgf_c_5
	v_add_u32_e32 v6, 0xdc00, v0
	global_load_dword v84, v6, s[100:101]
	v_add_u32_e32 v6, 0x10800, v0
	global_load_dword v86, v6, s[100:101]
	v_add_u32_e32 v6, 0x16000, v0
	global_load_dword v85, v6, s[100:101]
	v_add_u32_e32 v6, 0x13400, v0
	global_load_dword v87, v6, s[100:101]
.Lgf_c_5:
.Lgf_ld_done:
	s_mov_b64 exec, s[34:35]
	s_waitcnt vmcnt(0)
	s_and_b64 vcc, exec, s[38:39]
	s_cbranch_vccz .Lgf_h2c_0
	v_pk_mul_f32 v[20:21], v[16:17], v[20:21]
	s_nop 0
	v_fma_f32 v22, v18, v22, v20
	v_add_f32_e32 v22, v22, v21
	v_add_f32_e32 v22, v19, v22
	v_mul_f32_e32 v20, v22, v22
	v_fmamk_f32 v20, v20, 0xbdd2d3e8, v216
	v_mul_f32_e32 v20, v22, v20
	v_exp_f32_e32 v20, v20
	s_nop 0
	v_add_f32_e32 v20, 1.0, v20
	v_rcp_f32_e32 v20, v20
	s_nop 0
	v_mul_f32_e32 v22, v22, v20
	v_mul_f32_e32 v22, v23, v22
	v_cvt_pk_bf16_f32 v22, v22, v179
	global_store_short v[2:3], v22, off
.Lgf_h2c_0:
	s_and_b64 vcc, exec, s[40:41]
	s_cbranch_vccz .Lgf_n_0
	v_pk_mul_f32 v[24:25], v[16:17], v[24:25]
	s_nop 0
	v_fma_f32 v26, v18, v26, v24
	v_add_f32_e32 v26, v26, v25
	v_add_f32_e32 v26, v19, v26
	v_mul_f32_e32 v24, v26, v26
	v_fmamk_f32 v24, v24, 0xbdd2d3e8, v216
	v_mul_f32_e32 v24, v26, v24
	v_exp_f32_e32 v24, v24
	s_nop 0
	v_add_f32_e32 v24, 1.0, v24
	v_rcp_f32_e32 v24, v24
	s_nop 0
	v_mul_f32_e32 v26, v26, v24
	v_mul_f32_e32 v26, v27, v26
	v_cvt_pk_bf16_f32 v26, v26, v179
	v_add_co_u32_e32 v4, vcc, 0x15e000, v2
	s_nop 1
	v_addc_co_u32_e32 v5, vcc, 0, v3, vcc
	global_store_short v[4:5], v26, off offset:2560
.Lgf_n_0:
	v_add_co_u32_e32 v2, vcc, 0x400, v2
	s_nop 1
	v_addc_co_u32_e32 v3, vcc, 0, v3, vcc
	s_and_b64 vcc, exec, s[38:39]
	s_cbranch_vccz .Lgf_h2c_1
	v_pk_mul_f32 v[32:33], v[28:29], v[32:33]
	s_nop 0
	v_fma_f32 v34, v30, v34, v32
	v_add_f32_e32 v34, v34, v33
	v_add_f32_e32 v34, v31, v34
	v_mul_f32_e32 v32, v34, v34
	v_fmamk_f32 v32, v32, 0xbdd2d3e8, v216
	v_mul_f32_e32 v32, v34, v32
	v_exp_f32_e32 v32, v32
	s_nop 0
	v_add_f32_e32 v32, 1.0, v32
	v_rcp_f32_e32 v32, v32
	s_nop 0
	v_mul_f32_e32 v34, v34, v32
	v_mul_f32_e32 v34, v35, v34
	v_cvt_pk_bf16_f32 v34, v34, v179
	global_store_short v[2:3], v34, off
.Lgf_h2c_1:
	s_and_b64 vcc, exec, s[40:41]
	s_cbranch_vccz .Lgf_n_1
	v_pk_mul_f32 v[36:37], v[28:29], v[36:37]
	s_nop 0
	v_fma_f32 v38, v30, v38, v36
	v_add_f32_e32 v38, v38, v37
	v_add_f32_e32 v38, v31, v38
	v_mul_f32_e32 v36, v38, v38
	v_fmamk_f32 v36, v36, 0xbdd2d3e8, v216
	v_mul_f32_e32 v36, v38, v36
	v_exp_f32_e32 v36, v36
	s_nop 0
	v_add_f32_e32 v36, 1.0, v36
	v_rcp_f32_e32 v36, v36
	s_nop 0
	v_mul_f32_e32 v38, v38, v36
	v_mul_f32_e32 v38, v39, v38
	v_cvt_pk_bf16_f32 v38, v38, v179
	v_add_co_u32_e32 v4, vcc, 0x15e000, v2
	s_nop 1
	v_addc_co_u32_e32 v5, vcc, 0, v3, vcc
	global_store_short v[4:5], v38, off offset:2560
.Lgf_n_1:
	v_add_co_u32_e32 v2, vcc, 0x400, v2
	s_nop 1
	v_addc_co_u32_e32 v3, vcc, 0, v3, vcc
	s_and_b64 vcc, exec, s[38:39]
	s_cbranch_vccz .Lgf_h2c_2
	v_pk_mul_f32 v[44:45], v[40:41], v[44:45]
	s_nop 0
	v_fma_f32 v46, v42, v46, v44
	v_add_f32_e32 v46, v46, v45
	v_add_f32_e32 v46, v43, v46
	v_mul_f32_e32 v44, v46, v46
	v_fmamk_f32 v44, v44, 0xbdd2d3e8, v216
	v_mul_f32_e32 v44, v46, v44
	v_exp_f32_e32 v44, v44
	s_nop 0
	v_add_f32_e32 v44, 1.0, v44
	v_rcp_f32_e32 v44, v44
	s_nop 0
	v_mul_f32_e32 v46, v46, v44
	v_mul_f32_e32 v46, v47, v46
	v_cvt_pk_bf16_f32 v46, v46, v179
	global_store_short v[2:3], v46, off
.Lgf_h2c_2:
	s_and_b64 vcc, exec, s[40:41]
	s_cbranch_vccz .Lgf_n_2
	v_pk_mul_f32 v[48:49], v[40:41], v[48:49]
	s_nop 0
	v_fma_f32 v50, v42, v50, v48
	v_add_f32_e32 v50, v50, v49
	v_add_f32_e32 v50, v43, v50
	v_mul_f32_e32 v48, v50, v50
	v_fmamk_f32 v48, v48, 0xbdd2d3e8, v216
	v_mul_f32_e32 v48, v50, v48
	v_exp_f32_e32 v48, v48
	s_nop 0
	v_add_f32_e32 v48, 1.0, v48
	v_rcp_f32_e32 v48, v48
	s_nop 0
	v_mul_f32_e32 v50, v50, v48
	v_mul_f32_e32 v50, v51, v50
	v_cvt_pk_bf16_f32 v50, v50, v179
	v_add_co_u32_e32 v4, vcc, 0x15e000, v2
	s_nop 1
	v_addc_co_u32_e32 v5, vcc, 0, v3, vcc
	global_store_short v[4:5], v50, off offset:2560
.Lgf_n_2:
	v_add_co_u32_e32 v2, vcc, 0x400, v2
	s_nop 1
	v_addc_co_u32_e32 v3, vcc, 0, v3, vcc
	s_and_b64 vcc, exec, s[38:39]
	s_cbranch_vccz .Lgf_h2c_3
	v_pk_mul_f32 v[56:57], v[52:53], v[56:57]
	s_nop 0
	v_fma_f32 v58, v54, v58, v56
	v_add_f32_e32 v58, v58, v57
	v_add_f32_e32 v58, v55, v58
	v_mul_f32_e32 v56, v58, v58
	v_fmamk_f32 v56, v56, 0xbdd2d3e8, v216
	v_mul_f32_e32 v56, v58, v56
	v_exp_f32_e32 v56, v56
	s_nop 0
	v_add_f32_e32 v56, 1.0, v56
	v_rcp_f32_e32 v56, v56
	s_nop 0
	v_mul_f32_e32 v58, v58, v56
	v_mul_f32_e32 v58, v59, v58
	v_cvt_pk_bf16_f32 v58, v58, v179
	global_store_short v[2:3], v58, off
.Lgf_h2c_3:
	s_and_b64 vcc, exec, s[40:41]
	s_cbranch_vccz .Lgf_n_3
	v_pk_mul_f32 v[60:61], v[52:53], v[60:61]
	s_nop 0
	v_fma_f32 v62, v54, v62, v60
	v_add_f32_e32 v62, v62, v61
	v_add_f32_e32 v62, v55, v62
	v_mul_f32_e32 v60, v62, v62
	v_fmamk_f32 v60, v60, 0xbdd2d3e8, v216
	v_mul_f32_e32 v60, v62, v60
	v_exp_f32_e32 v60, v60
	s_nop 0
	v_add_f32_e32 v60, 1.0, v60
	v_rcp_f32_e32 v60, v60
	s_nop 0
	v_mul_f32_e32 v62, v62, v60
	v_mul_f32_e32 v62, v63, v62
	v_cvt_pk_bf16_f32 v62, v62, v179
	v_add_co_u32_e32 v4, vcc, 0x15e000, v2
	s_nop 1
	v_addc_co_u32_e32 v5, vcc, 0, v3, vcc
	global_store_short v[4:5], v62, off offset:2560
.Lgf_n_3:
	v_add_co_u32_e32 v2, vcc, 0x400, v2
	s_nop 1
	v_addc_co_u32_e32 v3, vcc, 0, v3, vcc
	s_and_b64 vcc, exec, s[38:39]
	s_cbranch_vccz .Lgf_h2c_4
	v_pk_mul_f32 v[68:69], v[64:65], v[68:69]
	s_nop 0
	v_fma_f32 v70, v66, v70, v68
	v_add_f32_e32 v70, v70, v69
	v_add_f32_e32 v70, v67, v70
	v_mul_f32_e32 v68, v70, v70
	v_fmamk_f32 v68, v68, 0xbdd2d3e8, v216
	v_mul_f32_e32 v68, v70, v68
	v_exp_f32_e32 v68, v68
	s_nop 0
	v_add_f32_e32 v68, 1.0, v68
	v_rcp_f32_e32 v68, v68
	s_nop 0
	v_mul_f32_e32 v70, v70, v68
	v_mul_f32_e32 v70, v71, v70
	v_cvt_pk_bf16_f32 v70, v70, v179
	global_store_short v[2:3], v70, off
.Lgf_h2c_4:
	s_and_b64 vcc, exec, s[40:41]
	s_cbranch_vccz .Lgf_n_4
	v_pk_mul_f32 v[72:73], v[64:65], v[72:73]
	s_nop 0
	v_fma_f32 v74, v66, v74, v72
	v_add_f32_e32 v74, v74, v73
	v_add_f32_e32 v74, v67, v74
	v_mul_f32_e32 v72, v74, v74
	v_fmamk_f32 v72, v72, 0xbdd2d3e8, v216
	v_mul_f32_e32 v72, v74, v72
	v_exp_f32_e32 v72, v72
	s_nop 0
	v_add_f32_e32 v72, 1.0, v72
	v_rcp_f32_e32 v72, v72
	s_nop 0
	v_mul_f32_e32 v74, v74, v72
	v_mul_f32_e32 v74, v75, v74
	v_cvt_pk_bf16_f32 v74, v74, v179
	v_add_co_u32_e32 v4, vcc, 0x15e000, v2
	s_nop 1
	v_addc_co_u32_e32 v5, vcc, 0, v3, vcc
	global_store_short v[4:5], v74, off offset:2560
.Lgf_n_4:
	v_add_co_u32_e32 v2, vcc, 0x400, v2
	s_nop 1
	v_addc_co_u32_e32 v3, vcc, 0, v3, vcc
	v_cmp_gt_u32_e32 vcc, 0x100, v192
	s_nop 1
	s_and_b64 exec, exec, vcc
	s_cbranch_execz .Lgf_done
	s_and_b64 vcc, exec, s[38:39]
	s_cbranch_vccz .Lgf_h2c_5
	v_pk_mul_f32 v[80:81], v[76:77], v[80:81]
	s_nop 0
	v_fma_f32 v82, v78, v82, v80
	v_add_f32_e32 v82, v82, v81
	v_add_f32_e32 v82, v79, v82
	v_mul_f32_e32 v80, v82, v82
	v_fmamk_f32 v80, v80, 0xbdd2d3e8, v216
	v_mul_f32_e32 v80, v82, v80
	v_exp_f32_e32 v80, v80
	s_nop 0
	v_add_f32_e32 v80, 1.0, v80
	v_rcp_f32_e32 v80, v80
	s_nop 0
	v_mul_f32_e32 v82, v82, v80
	v_mul_f32_e32 v82, v83, v82
	v_cvt_pk_bf16_f32 v82, v82, v179
	global_store_short v[2:3], v82, off
.Lgf_h2c_5:
	s_and_b64 vcc, exec, s[40:41]
	s_cbranch_vccz .Lgf_n_5
	v_pk_mul_f32 v[84:85], v[76:77], v[84:85]
	s_nop 0
	v_fma_f32 v86, v78, v86, v84
	v_add_f32_e32 v86, v86, v85
	v_add_f32_e32 v86, v79, v86
	v_mul_f32_e32 v84, v86, v86
	v_fmamk_f32 v84, v84, 0xbdd2d3e8, v216
	v_mul_f32_e32 v84, v86, v84
	v_exp_f32_e32 v84, v84
	s_nop 0
	v_add_f32_e32 v84, 1.0, v84
	v_rcp_f32_e32 v84, v84
	s_nop 0
	v_mul_f32_e32 v86, v86, v84
	v_mul_f32_e32 v86, v87, v86
	v_cvt_pk_bf16_f32 v86, v86, v179
	v_add_co_u32_e32 v4, vcc, 0x15e000, v2
	s_nop 1
	v_addc_co_u32_e32 v5, vcc, 0, v3, vcc
	global_store_short v[4:5], v86, off offset:2560

.LBB0_821:
	s_add_i32 vcc_lo, s60, 2
	s_add_u32 s44, s86, s88
	s_addc_u32 s45, s87, s89
	s_add_u32 s54, s84, s88
	s_addc_u32 vcc_hi, s85, s89
	s_add_i32 s56, 0, 0x10000
	s_cmp_eq_u32 s49, s60
	s_cselect_b32 s61, s41, s45
	s_cselect_b32 s60, s40, s44
	s_cselect_b32 s45, s83, vcc_hi
	s_cselect_b32 s44, s82, s54
	s_add_i32 s54, 0, 0x14000
	v_add_u32_e32 v152, s56, v138
	v_add_u32_e32 v161, s54, v138
	ds_read_b128 v[140:143], v152
	ds_read_b128 v[144:147], v152 offset:1024
	ds_read_b128 v[148:151], v152 offset:2048
	ds_read_b128 v[152:155], v152 offset:3072
	ds_read_b128 v[156:159], v161
	ds_read_b128 v[162:165], v161 offset:1024
	ds_read_b128 v[166:169], v161 offset:2048
	ds_read_b128 v[170:173], v161 offset:3072
	v_lshl_add_u64 v[184:185], s[86:87], 0, v[136:137]
	s_add_i32 m0, s63, 0xc000
	ds_read_b128 v[174:177], v139
	ds_read_b128 v[194:197], v139 offset:1024
	ds_read_b128 v[198:201], v139 offset:2048
	ds_read_b128 v[202:205], v139 offset:3072
	ds_read_b128 v[206:209], v139 offset:4096
	ds_read_b128 v[210:213], v139 offset:5120
	ds_read_b128 v[226:229], v139 offset:6144
	ds_read_b128 v[230:233], v139 offset:7168
	global_load_lds_dwordx4 v[184:185], off
	v_lshl_add_u64 v[184:185], s[86:87], 0, v[134:135]
	s_add_i32 m0, s63, 0xe000
	s_nop 0
	global_load_lds_dwordx4 v[184:185], off
	s_waitcnt vmcnt(8)
	s_waitcnt lgkmcnt(0)
	s_barrier
	s_setprio 1
	s_waitcnt lgkmcnt(0)
	v_mfma_f32_16x16x32_bf16 v[124:127], v[140:143], v[174:177], v[124:127]
	v_mfma_f32_16x16x32_bf16 v[120:123], v[148:151], v[174:177], v[120:123]
	v_mfma_f32_16x16x32_bf16 v[108:111], v[140:143], v[198:201], v[108:111]
	v_mfma_f32_16x16x32_bf16 v[104:107], v[148:151], v[198:201], v[104:107]
	v_mfma_f32_16x16x32_bf16 v[96:99], v[140:143], v[206:209], v[96:99]
	v_mfma_f32_16x16x32_bf16 v[88:91], v[148:151], v[206:209], v[88:91]
	v_mfma_f32_16x16x32_bf16 v[80:83], v[140:143], v[226:229], v[80:83]
	v_mfma_f32_16x16x32_bf16 v[72:75], v[148:151], v[226:229], v[72:75]
	v_mfma_f32_16x16x32_bf16 v[124:127], v[144:147], v[194:197], v[124:127]
	v_mfma_f32_16x16x32_bf16 v[120:123], v[152:155], v[194:197], v[120:123]
	v_mfma_f32_16x16x32_bf16 v[108:111], v[144:147], v[202:205], v[108:111]
	v_mfma_f32_16x16x32_bf16 v[104:107], v[152:155], v[202:205], v[104:107]
	v_mfma_f32_16x16x32_bf16 v[96:99], v[144:147], v[210:213], v[96:99]
	v_mfma_f32_16x16x32_bf16 v[88:91], v[152:155], v[210:213], v[88:91]
	v_mfma_f32_16x16x32_bf16 v[80:83], v[144:147], v[230:233], v[80:83]
	v_mfma_f32_16x16x32_bf16 v[72:75], v[152:155], v[230:233], v[72:75]
	s_setprio 0
	s_setprio 1
	v_mfma_f32_16x16x32_bf16 v[116:119], v[156:159], v[174:177], v[116:119]
	v_mfma_f32_16x16x32_bf16 v[112:115], v[166:169], v[174:177], v[112:115]
	v_mfma_f32_16x16x32_bf16 v[100:103], v[156:159], v[198:201], v[100:103]
	v_mfma_f32_16x16x32_bf16 v[92:95], v[166:169], v[198:201], v[92:95]
	v_mfma_f32_16x16x32_bf16 v[84:87], v[156:159], v[206:209], v[84:87]
	v_mfma_f32_16x16x32_bf16 v[76:79], v[166:169], v[206:209], v[76:79]
	v_mfma_f32_16x16x32_bf16 v[68:71], v[156:159], v[226:229], v[68:71]
	v_mfma_f32_16x16x32_bf16 v[60:63], v[166:169], v[226:229], v[60:63]
	v_mfma_f32_16x16x32_bf16 v[116:119], v[162:165], v[194:197], v[116:119]
	v_mfma_f32_16x16x32_bf16 v[112:115], v[170:173], v[194:197], v[112:115]
	v_mfma_f32_16x16x32_bf16 v[100:103], v[162:165], v[202:205], v[100:103]
	v_mfma_f32_16x16x32_bf16 v[92:95], v[170:173], v[202:205], v[92:95]
	v_mfma_f32_16x16x32_bf16 v[84:87], v[162:165], v[210:213], v[84:87]
	v_mfma_f32_16x16x32_bf16 v[76:79], v[170:173], v[210:213], v[76:79]
	v_mfma_f32_16x16x32_bf16 v[68:71], v[162:165], v[230:233], v[68:71]
	v_mfma_f32_16x16x32_bf16 v[60:63], v[170:173], v[230:233], v[60:63]
	s_setprio 0
	s_barrier
	s_add_i32 s56, s56, s58
	v_lshl_add_u64 v[184:185], s[44:45], 0, v[178:179]
	s_mov_b32 m0, s56
	ds_read_b128 v[174:177], v139 offset:16384
	ds_read_b128 v[194:197], v139 offset:17408
	ds_read_b128 v[198:201], v139 offset:18432
	ds_read_b128 v[202:205], v139 offset:19456
	ds_read_b128 v[206:209], v139 offset:20480
	ds_read_b128 v[210:213], v139 offset:21504
	ds_read_b128 v[226:229], v139 offset:22528
	ds_read_b128 v[230:233], v139 offset:23552
	global_load_lds_dwordx4 v[184:185], off
	s_add_i32 m0, s56, 0x2000
	v_lshl_add_u64 v[234:235], s[44:45], 0, v[128:129]
	s_add_u32 s44, s44, s23
	s_addc_u32 s45, s45, 0
	s_add_i32 s54, s54, s58
	global_load_lds_dwordx4 v[234:235], off
	v_lshl_add_u64 v[236:237], s[44:45], 0, v[178:179]
	s_mov_b32 m0, s54
	v_lshl_add_u64 v[238:239], s[44:45], 0, v[128:129]
	global_load_lds_dwordx4 v[236:237], off
	s_add_i32 m0, s54, 0x2000
	v_lshl_add_u64 v[240:241], s[60:61], 0, v[178:179]
	global_load_lds_dwordx4 v[238:239], off
	s_mov_b32 m0, s63
	v_lshl_add_u64 v[242:243], s[60:61], 0, v[128:129]
	global_load_lds_dwordx4 v[240:241], off
	s_mov_b32 m0, s91
	s_nop 0
	global_load_lds_dwordx4 v[242:243], off
	s_waitcnt vmcnt(8)
	s_waitcnt lgkmcnt(0)
	s_barrier
	s_setprio 1
	s_waitcnt lgkmcnt(0)
	v_mfma_f32_16x16x32_bf16 v[64:67], v[140:143], v[174:177], v[64:67]
	v_mfma_f32_16x16x32_bf16 v[56:59], v[148:151], v[174:177], v[56:59]
	v_mfma_f32_16x16x32_bf16 v[48:51], v[140:143], v[198:201], v[48:51]
	v_mfma_f32_16x16x32_bf16 v[40:43], v[148:151], v[198:201], v[40:43]
	v_mfma_f32_16x16x32_bf16 v[28:31], v[140:143], v[206:209], v[28:31]
	v_mfma_f32_16x16x32_bf16 v[24:27], v[148:151], v[206:209], v[24:27]
	v_mfma_f32_16x16x32_bf16 v[12:15], v[140:143], v[226:229], v[12:15]
	v_mfma_f32_16x16x32_bf16 v[8:11], v[148:151], v[226:229], v[8:11]
	v_mfma_f32_16x16x32_bf16 v[64:67], v[144:147], v[194:197], v[64:67]
	v_mfma_f32_16x16x32_bf16 v[56:59], v[152:155], v[194:197], v[56:59]
	v_mfma_f32_16x16x32_bf16 v[48:51], v[144:147], v[202:205], v[48:51]
	v_mfma_f32_16x16x32_bf16 v[40:43], v[152:155], v[202:205], v[40:43]
	v_mfma_f32_16x16x32_bf16 v[28:31], v[144:147], v[210:213], v[28:31]
	v_mfma_f32_16x16x32_bf16 v[24:27], v[152:155], v[210:213], v[24:27]
	v_mfma_f32_16x16x32_bf16 v[12:15], v[144:147], v[230:233], v[12:15]
	v_mfma_f32_16x16x32_bf16 v[8:11], v[152:155], v[230:233], v[8:11]
	s_setprio 0
	s_setprio 1
	v_mfma_f32_16x16x32_bf16 v[52:55], v[156:159], v[174:177], v[52:55]
	v_mfma_f32_16x16x32_bf16 v[44:47], v[166:169], v[174:177], v[44:47]
	v_mfma_f32_16x16x32_bf16 v[36:39], v[156:159], v[198:201], v[36:39]
	v_mfma_f32_16x16x32_bf16 v[32:35], v[166:169], v[198:201], v[32:35]
	v_mfma_f32_16x16x32_bf16 v[20:23], v[156:159], v[206:209], v[20:23]
	v_mfma_f32_16x16x32_bf16 v[16:19], v[166:169], v[206:209], v[16:19]
	v_mfma_f32_16x16x32_bf16 v[4:7], v[156:159], v[226:229], v[4:7]
	v_mfma_f32_16x16x32_bf16 v[0:3], v[166:169], v[226:229], v[0:3]
	v_mfma_f32_16x16x32_bf16 v[52:55], v[162:165], v[194:197], v[52:55]
	v_mfma_f32_16x16x32_bf16 v[44:47], v[170:173], v[194:197], v[44:47]
	v_mfma_f32_16x16x32_bf16 v[36:39], v[162:165], v[202:205], v[36:39]
	v_mfma_f32_16x16x32_bf16 v[32:35], v[170:173], v[202:205], v[32:35]
	v_mfma_f32_16x16x32_bf16 v[20:23], v[162:165], v[210:213], v[20:23]
	v_mfma_f32_16x16x32_bf16 v[16:19], v[170:173], v[210:213], v[16:19]
	v_mfma_f32_16x16x32_bf16 v[4:7], v[162:165], v[230:233], v[4:7]
	v_mfma_f32_16x16x32_bf16 v[0:3], v[170:173], v[230:233], v[0:3]
	s_setprio 0
	s_barrier
	s_add_i32 s54, 0, 0x18000
	s_add_i32 s56, 0, 0x1c000
	v_add_u32_e32 v152, s54, v138
	v_add_u32_e32 v161, s56, v138
	ds_read_b128 v[140:143], v152
	ds_read_b128 v[144:147], v152 offset:1024
	ds_read_b128 v[148:151], v152 offset:2048
	ds_read_b128 v[152:155], v152 offset:3072
	ds_read_b128 v[156:159], v161
	ds_read_b128 v[162:165], v161 offset:1024
	ds_read_b128 v[166:169], v161 offset:2048
	ds_read_b128 v[170:173], v161 offset:3072
	s_add_u32 s44, s60, s23
	s_addc_u32 s45, s61, 0
	s_mov_b32 m0, s92
	v_lshl_add_u64 v[244:245], s[44:45], 0, v[178:179]
	ds_read_b128 v[174:177], v139 offset:32768
	ds_read_b128 v[194:197], v139 offset:33792
	ds_read_b128 v[198:201], v139 offset:34816
	ds_read_b128 v[202:205], v139 offset:35840
	ds_read_b128 v[206:209], v139 offset:36864
	ds_read_b128 v[210:213], v139 offset:37888
	ds_read_b128 v[226:229], v139 offset:38912
	ds_read_b128 v[230:233], v139 offset:39936
	global_load_lds_dwordx4 v[244:245], off
	v_lshl_add_u64 v[244:245], s[44:45], 0, v[128:129]
	s_mov_b32 m0, s93
	s_nop 0
	global_load_lds_dwordx4 v[244:245], off
	s_waitcnt vmcnt(8)
	s_waitcnt lgkmcnt(0)
	s_barrier
	s_setprio 1
	s_waitcnt lgkmcnt(0)
	v_mfma_f32_16x16x32_bf16 v[124:127], v[140:143], v[174:177], v[124:127]
	v_mfma_f32_16x16x32_bf16 v[120:123], v[148:151], v[174:177], v[120:123]
	v_mfma_f32_16x16x32_bf16 v[108:111], v[140:143], v[198:201], v[108:111]
	v_mfma_f32_16x16x32_bf16 v[104:107], v[148:151], v[198:201], v[104:107]
	v_mfma_f32_16x16x32_bf16 v[96:99], v[140:143], v[206:209], v[96:99]
	v_mfma_f32_16x16x32_bf16 v[88:91], v[148:151], v[206:209], v[88:91]
	v_mfma_f32_16x16x32_bf16 v[80:83], v[140:143], v[226:229], v[80:83]
	v_mfma_f32_16x16x32_bf16 v[72:75], v[148:151], v[226:229], v[72:75]
	v_mfma_f32_16x16x32_bf16 v[124:127], v[144:147], v[194:197], v[124:127]
	v_mfma_f32_16x16x32_bf16 v[120:123], v[152:155], v[194:197], v[120:123]
	v_mfma_f32_16x16x32_bf16 v[108:111], v[144:147], v[202:205], v[108:111]
	v_mfma_f32_16x16x32_bf16 v[104:107], v[152:155], v[202:205], v[104:107]
	v_mfma_f32_16x16x32_bf16 v[96:99], v[144:147], v[210:213], v[96:99]
	v_mfma_f32_16x16x32_bf16 v[88:91], v[152:155], v[210:213], v[88:91]
	v_mfma_f32_16x16x32_bf16 v[80:83], v[144:147], v[230:233], v[80:83]
	v_mfma_f32_16x16x32_bf16 v[72:75], v[152:155], v[230:233], v[72:75]
	s_setprio 0
	s_setprio 1
	v_mfma_f32_16x16x32_bf16 v[116:119], v[156:159], v[174:177], v[116:119]
	v_mfma_f32_16x16x32_bf16 v[112:115], v[166:169], v[174:177], v[112:115]
	v_mfma_f32_16x16x32_bf16 v[100:103], v[156:159], v[198:201], v[100:103]
	v_mfma_f32_16x16x32_bf16 v[92:95], v[166:169], v[198:201], v[92:95]
	v_mfma_f32_16x16x32_bf16 v[84:87], v[156:159], v[206:209], v[84:87]
	v_mfma_f32_16x16x32_bf16 v[76:79], v[166:169], v[206:209], v[76:79]
	v_mfma_f32_16x16x32_bf16 v[68:71], v[156:159], v[226:229], v[68:71]
	v_mfma_f32_16x16x32_bf16 v[60:63], v[166:169], v[226:229], v[60:63]
	v_mfma_f32_16x16x32_bf16 v[116:119], v[162:165], v[194:197], v[116:119]
	v_mfma_f32_16x16x32_bf16 v[112:115], v[170:173], v[194:197], v[112:115]
	v_mfma_f32_16x16x32_bf16 v[100:103], v[162:165], v[202:205], v[100:103]
	v_mfma_f32_16x16x32_bf16 v[92:95], v[170:173], v[202:205], v[92:95]
	v_mfma_f32_16x16x32_bf16 v[84:87], v[162:165], v[210:213], v[84:87]
	v_mfma_f32_16x16x32_bf16 v[76:79], v[170:173], v[210:213], v[76:79]
	v_mfma_f32_16x16x32_bf16 v[68:71], v[162:165], v[230:233], v[68:71]
	v_mfma_f32_16x16x32_bf16 v[60:63], v[170:173], v[230:233], v[60:63]
	s_setprio 0
	s_barrier
	s_add_i32 s44, s54, s58
	v_lshl_add_u64 v[184:185], v[184:185], 0, s[28:29]
	s_mov_b32 m0, s44
	ds_read_b128 v[174:177], v139 offset:49152
	ds_read_b128 v[194:197], v139 offset:50176
	ds_read_b128 v[198:201], v139 offset:51200
	ds_read_b128 v[202:205], v139 offset:52224
	ds_read_b128 v[206:209], v139 offset:53248
	ds_read_b128 v[210:213], v139 offset:54272
	ds_read_b128 v[226:229], v139 offset:55296
	ds_read_b128 v[230:233], v139 offset:56320
	global_load_lds_dwordx4 v[184:185], off
	v_lshl_add_u64 v[184:185], v[234:235], 0, s[28:29]
	s_add_i32 m0, s44, 0x2000
	s_add_i32 s44, s56, s58
	global_load_lds_dwordx4 v[184:185], off
	v_lshl_add_u64 v[184:185], v[236:237], 0, s[28:29]
	s_mov_b32 m0, s44
	s_nop 0
	global_load_lds_dwordx4 v[184:185], off
	v_lshl_add_u64 v[184:185], v[238:239], 0, s[28:29]
	s_add_i32 m0, s44, 0x2000
	s_nop 0
	global_load_lds_dwordx4 v[184:185], off
	v_lshl_add_u64 v[184:185], v[240:241], 0, s[28:29]
	s_mov_b32 m0, s94
	s_nop 0
	global_load_lds_dwordx4 v[184:185], off
	v_lshl_add_u64 v[184:185], v[242:243], 0, s[28:29]
	s_mov_b32 m0, s95
	s_nop 0
	global_load_lds_dwordx4 v[184:185], off
	s_waitcnt vmcnt(8)
	s_waitcnt lgkmcnt(0)
	s_barrier
	s_setprio 1
	s_waitcnt lgkmcnt(0)
	v_mfma_f32_16x16x32_bf16 v[64:67], v[140:143], v[174:177], v[64:67]
	v_mfma_f32_16x16x32_bf16 v[56:59], v[148:151], v[174:177], v[56:59]
	v_mfma_f32_16x16x32_bf16 v[48:51], v[140:143], v[198:201], v[48:51]
	v_mfma_f32_16x16x32_bf16 v[40:43], v[148:151], v[198:201], v[40:43]
	v_mfma_f32_16x16x32_bf16 v[28:31], v[140:143], v[206:209], v[28:31]
	v_mfma_f32_16x16x32_bf16 v[24:27], v[148:151], v[206:209], v[24:27]
	v_mfma_f32_16x16x32_bf16 v[12:15], v[140:143], v[226:229], v[12:15]
	v_mfma_f32_16x16x32_bf16 v[8:11], v[148:151], v[226:229], v[8:11]
	v_mfma_f32_16x16x32_bf16 v[64:67], v[144:147], v[194:197], v[64:67]
	v_mfma_f32_16x16x32_bf16 v[56:59], v[152:155], v[194:197], v[56:59]
	v_mfma_f32_16x16x32_bf16 v[48:51], v[144:147], v[202:205], v[48:51]
	v_mfma_f32_16x16x32_bf16 v[40:43], v[152:155], v[202:205], v[40:43]
	v_mfma_f32_16x16x32_bf16 v[28:31], v[144:147], v[210:213], v[28:31]
	v_mfma_f32_16x16x32_bf16 v[24:27], v[152:155], v[210:213], v[24:27]
	v_mfma_f32_16x16x32_bf16 v[12:15], v[144:147], v[230:233], v[12:15]
	v_mfma_f32_16x16x32_bf16 v[8:11], v[152:155], v[230:233], v[8:11]
	s_setprio 0
	s_setprio 1
	v_mfma_f32_16x16x32_bf16 v[52:55], v[156:159], v[174:177], v[52:55]
	v_mfma_f32_16x16x32_bf16 v[44:47], v[166:169], v[174:177], v[44:47]
	v_mfma_f32_16x16x32_bf16 v[36:39], v[156:159], v[198:201], v[36:39]
	v_mfma_f32_16x16x32_bf16 v[32:35], v[166:169], v[198:201], v[32:35]
	v_mfma_f32_16x16x32_bf16 v[20:23], v[156:159], v[206:209], v[20:23]
	v_mfma_f32_16x16x32_bf16 v[16:19], v[166:169], v[206:209], v[16:19]
	v_mfma_f32_16x16x32_bf16 v[4:7], v[156:159], v[226:229], v[4:7]
	v_mfma_f32_16x16x32_bf16 v[0:3], v[166:169], v[226:229], v[0:3]
	v_mfma_f32_16x16x32_bf16 v[52:55], v[162:165], v[194:197], v[52:55]
	v_mfma_f32_16x16x32_bf16 v[44:47], v[170:173], v[194:197], v[44:47]
	v_mfma_f32_16x16x32_bf16 v[36:39], v[162:165], v[202:205], v[36:39]
	v_mfma_f32_16x16x32_bf16 v[32:35], v[170:173], v[202:205], v[32:35]
	v_mfma_f32_16x16x32_bf16 v[20:23], v[162:165], v[210:213], v[20:23]
	v_mfma_f32_16x16x32_bf16 v[16:19], v[170:173], v[210:213], v[16:19]
	v_mfma_f32_16x16x32_bf16 v[4:7], v[162:165], v[230:233], v[4:7]
	v_mfma_f32_16x16x32_bf16 v[0:3], v[170:173], v[230:233], v[0:3]
	s_setprio 0
	s_barrier
	s_add_i32 s98, s60, 4
	s_cmp_lg_u32 s98, s48
	s_cbranch_scc1 .Lxpf_skip
	v_lshrrev_b32_e32 v246, 5, v219
	v_bfe_u32 v247, v219, 4, 1
	v_lshl_add_u32 v246, v246, 4, v160
	v_lshlrev_b32_e32 v247, 9, v247
	s_lshl_b32 s100, s35, 7
	s_lshl_b32 s101, s62, 10
	s_add_u32 s100, s100, s101
	v_lshl_or_b32 v246, v246, 12, v247
	s_cmp_lt_i32 s22, 32
	v_add_u32_e32 v246, s100, v246
	s_cbranch_scc1 .Lxpf_lo
	v_readlane_b32 s98, v255, 18
	v_readlane_b32 s99, v255, 19
	s_sub_i32 s100, s22, 32
	s_branch .Lxpf_b
.Lxpf_lo:
	v_readlane_b32 s98, v255, 10
	v_readlane_b32 s99, v255, 11
	s_mov_b32 s100, s22
.Lxpf_b:
	s_lshr_b32 s101, s100, 12
	s_lshl_b32 s100, s100, 20
	s_add_u32 s98, s98, s100
	s_addc_u32 s99, s99, s101
	global_load_dword v225, v246, s[98:99]
	s_add_u32 s100, s98, 0x20000
	s_addc_u32 s101, s99, 0
	global_load_dword v225, v246, s[100:101]
	s_add_u32 s100, s98, 0x80000
	s_addc_u32 s101, s99, 0
	global_load_dword v225, v246, s[100:101]
	s_add_u32 s100, s98, 0xa0000
	s_addc_u32 s101, s99, 0
	global_load_dword v225, v246, s[100:101]
.Lxpf_skip:
	s_add_u32 s88, s88, 0x100
	s_addc_u32 s89, s89, 0
	v_lshl_add_u64 v[136:137], v[136:137], 0, s[30:31]
	v_lshl_add_u64 v[134:135], v[134:135], 0, s[30:31]
	s_cmp_ge_u32 vcc_lo, s48
	s_mov_b32 s60, vcc_lo
	s_cbranch_scc0 .LBB0_821
	s_and_b64 vcc, exec, s[80:81]
	s_cbranch_vccz .LBB0_824
	s_barrier
